# A/B: final stack without any static s_setprio raise
# baseline (speedup 1.0000x reference)
; __device__ __forceinline__ int otid() { int t = threadIdx.x; asm volatile("" : "+v"(t)); return t; }
; __global__ void __launch_bounds__(512) fwd_kernel(KArgs A0) {
;     ...
;     const int ph_lo = A0.ph_lo, ph_hi = A0.ph_hi;
;     if (ph_lo < 0) grid.sync();
;     for (int ph = ph_lo; ph < ph_hi; ++ph) {
;       {
;         const int tid_ = otid(); const int lane = tid_ & 63, wave = __builtin_amdgcn_readfirstlane(tid_ >> 6);
;         const KArgs __attribute__((address_space(4)))* ap_ = (const KArgs __attribute__((address_space(4)))*)__builtin_amdgcn_kernarg_segment_ptr();
;         asm volatile("" : "+s"(ap_));
;         const KArgs& A = *(const KArgs*)ap_;
;         unsigned char* ws = A.ws;
;     ...
;         if (ph == PH_PRO) { if (PM & 1) phase_prologue(A, ldsl, wave, lane); }
;         else if (ph == PH_ADA) phase_ada_reduce(A);
;         else if (ph == PH_L0_ROW || ph == PH_L1_ROW || ph == PH_L2_ROW || ph == PH_L3_ROW || ph == PH_FIN)
;             { if (PM & 2) phase_rowpass(A, ph == PH_L0_ROW ? 0 : ph == PH_L1_ROW ? 1 : ph == PH_L2_ROW ? 2 : ph == PH_L3_ROW ? 3 : 4, wave, lane); }
;         else if (ph == PH_L1_POST) { if (PM & 4) phase_post_gqa(A, wave, lane); }
;         else if (ph == PH_L2_POST) { if (PM & 4) phase_post_mla(A, wave, lane); }
;         else if (ph == PH_L0_ATT || ph == PH_L3_ATT) { if (PM & 8) phase_attn<64, 128, true, ATT_SD0, 0, ATT_NBUF>(A, (char*)lds, ph == PH_L0_ATT ? 0 : 3, ph == PH_L0_ATT, wave, lane); }
;         else if (ph == PH_L1_ATT) { if (PM & 16) phase_attn<128, 128, false, ATT_SD0, 4, ATT_NBUF>(A, (char*)lds, 1, true, wave, lane); }
;         else if (ph == PH_L2_ATT) { if (PM & 32) phase_attn<192, 192, false, 1, 3, ATT_NBUF>(A, (char*)lds, 2, true, wave, lane); }
;         else if (PM & 64) {
.LBB0_22:
	v_writelane_b32 v255, s40, 4
	v_mov_b32_e32 v191, v184
	s_mov_b64 s[56:57], s[44:45]
	v_writelane_b32 v255, s41, 5
	v_writelane_b32 v255, s42, 6
	s_waitcnt lgkmcnt(0)
	s_load_dwordx2 s[94:95], s[56:57], 0x168
	v_readfirstlane_b32 s2, v191
	v_writelane_b32 v255, s43, 7
	s_ashr_i32 s2, s2, 6
	v_writelane_b32 v255, s2, 8
	v_writelane_b32 v255, s56, 9
	s_mov_b32 s49, s42
	v_and_b32_e32 v190, 63, v191
	s_mov_b64 s[8:9], -1
	s_mov_b64 s[46:47], 0
	s_cmp_lt_i32 s42, 9
	s_mov_b64 s[6:7], 0
	s_mov_b64 s[98:99], 0
	s_mov_b64 s[4:5], 0
	s_mov_b32 s97, s42
	v_writelane_b32 v255, s57, 10
	s_cbranch_scc1 .LBB0_39
	s_cmp_gt_i32 s49, 15
	s_cbranch_scc0 .LBB0_73
	s_mov_b64 s[12:13], -1
	s_mov_b64 s[8:9], 0
	s_cmp_gt_i32 s49, 19
	s_mov_b64 s[10:11], 0
	s_cbranch_scc0 .LBB0_30
	s_cmp_gt_i32 s49, 21
	s_cbranch_scc0 .LBB0_27
	s_cmp_eq_u32 s49, 22
	s_mov_b64 s[12:13], 0
	s_mov_b64 s[6:7], -1
	s_cselect_b64 s[10:11], -1, 0
